# MLA prologue: K(1)/PE(1) loads merged into the first load batch; out-proj residual epilogue (fp16 path): the two x loads of a row issued together before one wait
# baseline (speedup 1.0000x reference)
; #define LOADK(t) do { const int kp_ = TILE_KPOS(t); kreg = *(const u32x4*)((const char*)P.K + (size_t)(koff + (unsigned)(kp_ * KPITCH * 2))); if (VAR == 0 && tid < 256) pereg = *(const u32x4*)((const char*)P.KPE + (size_t)(peoff + (unsigned)(kp_ * 64))); } while (0)
; #define LOADV(t) do { const int kp_ = TILE_KPOS(t); vreg = *(const u32x4*)((const char*)P.VT + (size_t)(voff + (unsigned)(kp_ * 2))); } while (0)
; #define STOREK(buf) do { LAS unsigned char* kb_ = lds + (buf) * ABUF; *(LAS u32x4*)(kb_ + (tid >> 3) * KP + (tid & 7) * 16) = kreg; \
;         if (VAR == 0 && tid < 256) *(LAS u32x4*)(kb_ + (tid >> 2) * KP + 128 + (tid & 3) * 16) = pereg; } while (0)
; #define STOREV(buf) do { *(LAS u32x4*)(lds + (buf) * ABUF + KT_BYTES + (tid >> 3) * VP + (tid & 7) * 16) = vreg; } while (0)
; template <int VAR>
; __device__ __forceinline__ void attn_phase(LAS unsigned char* lds, const AttnP P, int vcu, int G, int wave_s) {
;     ...
;         LOADK(0); LOADV(0); STOREK(0); STOREV(0);
;         if (nt > 1) { LOADK(1); STOREK(1); }
;         __syncthreads();
;         f32x16 pc0, pc1; const f32x16 zero16 = {};
;         QK_TILE(pc0, pc1, 0, zero16);
;         float mref = rowmax32(pc0, pc1), lrun = 0.f;
;         if (VAR == 1) { const float sk = P.sink[hq] * LOG2E; mref = __builtin_fmaxf(mref, sk); lrun = (hi == 0) ? __builtin_amdgcn_exp2f(sk - mref) : 0.f; }
;         f32x16 negm = {};
;         if (USE_NEGM) {
; #pragma unroll
;             for (int r = 0; r < 16; ++r) { pc0[r] -= mref; pc1[r] -= mref; negm[r] = -mref; }
;         }
;         float rmc = 0.f;
;         bool need_c = true;
;         __syncthreads();
;         for (int t = 0; t < nt; ++t) {
;             const bool hn = (t + 1 < nt);
;             if (hn) { const int t2 = (t + 2 < nt) ? t + 2 : nt - 1; LOADK(t2); LOADV(t + 1); }
.LBB0_1169:
	s_or_b64 exec, exec, s[0:1]
	s_lshl_b32 s0, s11, 10
	s_or_b32 s0, s0, s8
	v_add_u32_e32 v1, s0, v157
	s_movk_i32 s0, 0x2100
	v_mul_lo_u32 v2, v1, s0
	v_or_b32_e32 v2, v2, v156
	s_lshl_b32 s0, s12, 7
	v_lshl_add_u32 v2, v2, 1, s0
	global_load_dwordx4 v[8:11], v2, s[56:57]
	s_add_i32 s0, s10, 1
	s_cmp_ge_i32 s0, s9
	s_cselect_b32 s1, s9, 0
	s_sub_i32 s11, s0, s1
	v_lshl_add_u32 v222, s11, 17, v178
	global_load_dwordx4 v[146:149], v222, s[52:53]
	s_and_saveexec_b64 s[0:1], s[2:3]
	s_cbranch_execz .Lmla_pro_nope
	v_lshl_add_u32 v222, s11, 12, v179
	global_load_dwordx4 v[142:145], v222, s[62:63]
.Lmla_pro_nope:
	s_or_b64 exec, exec, s[0:1]
	s_waitcnt vmcnt(0)
	ds_write_b128 v172, v[4:7]
	ds_write_b128 v173, v[8:11] offset:13312
	ds_write_b128 v172, v[146:149] offset:22528
	s_and_saveexec_b64 s[0:1], s[2:3]
	ds_write_b128 v176, v[138:141] offset:128
	ds_write_b128 v176, v[142:145] offset:22656
	s_or_b64 exec, exec, s[0:1]
	s_waitcnt lgkmcnt(0)
	s_barrier
	s_add_i32 s19, s9, -1
	s_min_u32 s0, s19, 2
	s_add_i32 s0, s0, s10
	s_cmp_ge_i32 s0, s9
	s_cselect_b32 s1, s9, 0
	s_sub_i32 s13, s0, s1
	s_add_i32 s0, s10, 1
	s_cmp_ge_i32 s0, s9
	s_cselect_b32 s1, s9, 0
	s_sub_i32 s19, s0, s1
	s_and_saveexec_b64 s[0:1], s[2:3]
	s_cbranch_execz .Lmla_early_nope
	v_lshl_add_u32 v222, s13, 12, v179
	global_load_dwordx4 v[138:141], v222, s[62:63]

;     __device__ __forceinline__ void ldx8(size_t off, f32x4& a, f32x4& b) const {
;         if (xin32) { a = *(const f32x4*)(xin32 + off); b = *(const f32x4*)(xin32 + off + 4); }
;         else { const h16x8 h = *(const h16x8*)(xin16 + off); a = (f32x4){(float)h[0], (float)h[1], (float)h[2], (float)h[3]}; b = (f32x4){(float)h[4], (float)h[5], (float)h[6], (float)h[7]}; }
;     }
;     __device__ __forceinline__ void operator()(AccRef acc, const pg8::Unit& u, int wr, int wc, int fr_, int fq_) const {
;     ...
;         { const size_t xo_ = (size_t)row0 * DM + col0; ldx8(xo_, xc[0], xc[1]); ldx8(xo_ + 128, xc[2], xc[3]); }
; #pragma unroll
;         for (int r = 0; r < 8; ++r) {
;             const int ai = r >> 2, m = r & 3; const int row = row0 + 128 * ai + 16 * m;
;             if (r < 7) { const int rown = row0 + 128 * ((r + 1) >> 2) + 16 * ((r + 1) & 3); const size_t xo_ = (size_t)rown * DM + col0; ldx8(xo_, xn[0], xn[1]); ldx8(xo_ + 128, xn[2], xn[3]); }
.LBB0_1262:
	global_load_dwordx4 v[152:155], v[148:149], off
	global_load_dwordx4 v[148:151], v[148:149], off offset:256
	s_waitcnt vmcnt(0)
	v_cvt_f32_f16_e32 v176, v152
	v_cvt_f32_f16_sdwa v177, v152 dst_sel:DWORD dst_unused:UNUSED_PAD src0_sel:WORD_1
	v_cvt_f32_f16_e32 v178, v153
	v_cvt_f32_f16_sdwa v179, v153 dst_sel:DWORD dst_unused:UNUSED_PAD src0_sel:WORD_1
	v_cvt_f32_f16_e32 v172, v154
	v_cvt_f32_f16_sdwa v173, v154 dst_sel:DWORD dst_unused:UNUSED_PAD src0_sel:WORD_1
	v_cvt_f32_f16_e32 v174, v155
	v_cvt_f32_f16_sdwa v175, v155 dst_sel:DWORD dst_unused:UNUSED_PAD src0_sel:WORD_1

;     __device__ __forceinline__ void ldx8(size_t off, f32x4& a, f32x4& b) const {
;         if (xin32) { a = *(const f32x4*)(xin32 + off); b = *(const f32x4*)(xin32 + off + 4); }
;         else { const h16x8 h = *(const h16x8*)(xin16 + off); a = (f32x4){(float)h[0], (float)h[1], (float)h[2], (float)h[3]}; b = (f32x4){(float)h[4], (float)h[5], (float)h[6], (float)h[7]}; }
;     }
;     __device__ __forceinline__ void operator()(AccRef acc, const pg8::Unit& u, int wr, int wc, int fr_, int fq_) const {
;     ...
;         { const size_t xo_ = (size_t)row0 * DM + col0; ldx8(xo_, xc[0], xc[1]); ldx8(xo_ + 128, xc[2], xc[3]); }
; #pragma unroll
;         for (int r = 0; r < 8; ++r) {
;             const int ai = r >> 2, m = r & 3; const int row = row0 + 128 * ai + 16 * m;
;             if (r < 7) { const int rown = row0 + 128 * ((r + 1) >> 2) + 16 * ((r + 1) & 3); const size_t xo_ = (size_t)rown * DM + col0; ldx8(xo_, xn[0], xn[1]); ldx8(xo_ + 128, xn[2], xn[3]); }
.LBB0_1265:
	v_cvt_f32_f16_e32 v168, v148
	v_cvt_f32_f16_sdwa v169, v148 dst_sel:DWORD dst_unused:UNUSED_PAD src0_sel:WORD_1
	v_cvt_f32_f16_e32 v170, v149
	v_cvt_f32_f16_sdwa v171, v149 dst_sel:DWORD dst_unused:UNUSED_PAD src0_sel:WORD_1
	v_cvt_f32_f16_e32 v156, v150
	v_cvt_f32_f16_sdwa v157, v150 dst_sel:DWORD dst_unused:UNUSED_PAD src0_sel:WORD_1
	v_cvt_f32_f16_e32 v158, v151
	v_cvt_f32_f16_sdwa v159, v151 dst_sel:DWORD dst_unused:UNUSED_PAD src0_sel:WORD_1

;     __device__ __forceinline__ void ldx8(size_t off, f32x4& a, f32x4& b) const {
;         if (xin32) { a = *(const f32x4*)(xin32 + off); b = *(const f32x4*)(xin32 + off + 4); }
;         else { const h16x8 h = *(const h16x8*)(xin16 + off); a = (f32x4){(float)h[0], (float)h[1], (float)h[2], (float)h[3]}; b = (f32x4){(float)h[4], (float)h[5], (float)h[6], (float)h[7]}; }
;     }
;     __device__ __forceinline__ void operator()(AccRef acc, const pg8::Unit& u, int wr, int wc, int fr_, int fq_) const {
;     ...
;         { const size_t xo_ = (size_t)row0 * DM + col0; ldx8(xo_, xc[0], xc[1]); ldx8(xo_ + 128, xc[2], xc[3]); }
; #pragma unroll
;         for (int r = 0; r < 8; ++r) {
;             const int ai = r >> 2, m = r & 3; const int row = row0 + 128 * ai + 16 * m;
;             if (r < 7) { const int rown = row0 + 128 * ((r + 1) >> 2) + 16 * ((r + 1) & 3); const size_t xo_ = (size_t)rown * DM + col0; ldx8(xo_, xn[0], xn[1]); ldx8(xo_ + 128, xn[2], xn[3]); }
.LBB0_1268:
	global_load_dwordx4 v[148:151], v[224:225], off
	global_load_dwordx4 v[160:163], v[224:225], off offset:256
	s_waitcnt vmcnt(0)
	v_cvt_f32_f16_e32 v152, v148
	v_cvt_f32_f16_sdwa v153, v148 dst_sel:DWORD dst_unused:UNUSED_PAD src0_sel:WORD_1
	v_cvt_f32_f16_e32 v154, v149
	v_cvt_f32_f16_sdwa v155, v149 dst_sel:DWORD dst_unused:UNUSED_PAD src0_sel:WORD_1
	v_cvt_f32_f16_e32 v148, v150
	v_cvt_f32_f16_sdwa v149, v150 dst_sel:DWORD dst_unused:UNUSED_PAD src0_sel:WORD_1
	v_cvt_f32_f16_e32 v150, v151
	v_cvt_f32_f16_sdwa v151, v151 dst_sel:DWORD dst_unused:UNUSED_PAD src0_sel:WORD_1

;     __device__ __forceinline__ void ldx8(size_t off, f32x4& a, f32x4& b) const {
;         if (xin32) { a = *(const f32x4*)(xin32 + off); b = *(const f32x4*)(xin32 + off + 4); }
;         else { const h16x8 h = *(const h16x8*)(xin16 + off); a = (f32x4){(float)h[0], (float)h[1], (float)h[2], (float)h[3]}; b = (f32x4){(float)h[4], (float)h[5], (float)h[6], (float)h[7]}; }
;     }
;     __device__ __forceinline__ void operator()(AccRef acc, const pg8::Unit& u, int wr, int wc, int fr_, int fq_) const {
;     ...
;         { const size_t xo_ = (size_t)row0 * DM + col0; ldx8(xo_, xc[0], xc[1]); ldx8(xo_ + 128, xc[2], xc[3]); }
; #pragma unroll
;         for (int r = 0; r < 8; ++r) {
;             const int ai = r >> 2, m = r & 3; const int row = row0 + 128 * ai + 16 * m;
;             if (r < 7) { const int rown = row0 + 128 * ((r + 1) >> 2) + 16 * ((r + 1) & 3); const size_t xo_ = (size_t)rown * DM + col0; ldx8(xo_, xn[0], xn[1]); ldx8(xo_ + 128, xn[2], xn[3]); }
.LBB0_1271:
	v_cvt_f32_f16_e32 v164, v160
	v_cvt_f32_f16_sdwa v165, v160 dst_sel:DWORD dst_unused:UNUSED_PAD src0_sel:WORD_1
	v_cvt_f32_f16_e32 v166, v161
	v_cvt_f32_f16_sdwa v167, v161 dst_sel:DWORD dst_unused:UNUSED_PAD src0_sel:WORD_1
	v_cvt_f32_f16_e32 v160, v162
	v_cvt_f32_f16_sdwa v161, v162 dst_sel:DWORD dst_unused:UNUSED_PAD src0_sel:WORD_1
	v_cvt_f32_f16_e32 v162, v163
	v_cvt_f32_f16_sdwa v163, v163 dst_sel:DWORD dst_unused:UNUSED_PAD src0_sel:WORD_1

;     __device__ __forceinline__ void ldx8(size_t off, f32x4& a, f32x4& b) const {
;         if (xin32) { a = *(const f32x4*)(xin32 + off); b = *(const f32x4*)(xin32 + off + 4); }
;         else { const h16x8 h = *(const h16x8*)(xin16 + off); a = (f32x4){(float)h[0], (float)h[1], (float)h[2], (float)h[3]}; b = (f32x4){(float)h[4], (float)h[5], (float)h[6], (float)h[7]}; }
;     }
;     __device__ __forceinline__ void operator()(AccRef acc, const pg8::Unit& u, int wr, int wc, int fr_, int fq_) const {
;     ...
;         { const size_t xo_ = (size_t)row0 * DM + col0; ldx8(xo_, xc[0], xc[1]); ldx8(xo_ + 128, xc[2], xc[3]); }
; #pragma unroll
;         for (int r = 0; r < 8; ++r) {
;             const int ai = r >> 2, m = r & 3; const int row = row0 + 128 * ai + 16 * m;
;             if (r < 7) { const int rown = row0 + 128 * ((r + 1) >> 2) + 16 * ((r + 1) & 3); const size_t xo_ = (size_t)rown * DM + col0; ldx8(xo_, xn[0], xn[1]); ldx8(xo_ + 128, xn[2], xn[3]); }
.LBB0_1278:
	global_load_dwordx4 v[136:139], v[10:11], off
	global_load_dwordx4 v[10:13], v[10:11], off offset:256
	s_waitcnt vmcnt(0)
	v_cvt_f32_f16_e32 v140, v136
	v_cvt_f32_f16_sdwa v141, v136 dst_sel:DWORD dst_unused:UNUSED_PAD src0_sel:WORD_1
	v_cvt_f32_f16_e32 v142, v137
	v_cvt_f32_f16_sdwa v143, v137 dst_sel:DWORD dst_unused:UNUSED_PAD src0_sel:WORD_1
	v_cvt_f32_f16_e32 v136, v138
	v_cvt_f32_f16_sdwa v137, v138 dst_sel:DWORD dst_unused:UNUSED_PAD src0_sel:WORD_1
	v_cvt_f32_f16_e32 v138, v139
	v_cvt_f32_f16_sdwa v139, v139 dst_sel:DWORD dst_unused:UNUSED_PAD src0_sel:WORD_1

;     __device__ __forceinline__ void ldx8(size_t off, f32x4& a, f32x4& b) const {
;         if (xin32) { a = *(const f32x4*)(xin32 + off); b = *(const f32x4*)(xin32 + off + 4); }
;         else { const h16x8 h = *(const h16x8*)(xin16 + off); a = (f32x4){(float)h[0], (float)h[1], (float)h[2], (float)h[3]}; b = (f32x4){(float)h[4], (float)h[5], (float)h[6], (float)h[7]}; }
;     }
;     __device__ __forceinline__ void operator()(AccRef acc, const pg8::Unit& u, int wr, int wc, int fr_, int fq_) const {
;     ...
;         { const size_t xo_ = (size_t)row0 * DM + col0; ldx8(xo_, xc[0], xc[1]); ldx8(xo_ + 128, xc[2], xc[3]); }
; #pragma unroll
;         for (int r = 0; r < 8; ++r) {
;             const int ai = r >> 2, m = r & 3; const int row = row0 + 128 * ai + 16 * m;
;             if (r < 7) { const int rown = row0 + 128 * ((r + 1) >> 2) + 16 * ((r + 1) & 3); const size_t xo_ = (size_t)rown * DM + col0; ldx8(xo_, xn[0], xn[1]); ldx8(xo_ + 128, xn[2], xn[3]); }
.LBB0_1281:
	v_cvt_f32_f16_e32 v156, v10
	v_cvt_f32_f16_sdwa v157, v10 dst_sel:DWORD dst_unused:UNUSED_PAD src0_sel:WORD_1
	v_cvt_f32_f16_e32 v158, v11
	v_cvt_f32_f16_sdwa v159, v11 dst_sel:DWORD dst_unused:UNUSED_PAD src0_sel:WORD_1
	v_cvt_f32_f16_e32 v144, v12
	v_cvt_f32_f16_sdwa v145, v12 dst_sel:DWORD dst_unused:UNUSED_PAD src0_sel:WORD_1
	v_cvt_f32_f16_e32 v146, v13
	v_cvt_f32_f16_sdwa v147, v13 dst_sel:DWORD dst_unused:UNUSED_PAD src0_sel:WORD_1

;     __device__ __forceinline__ void ldx8(size_t off, f32x4& a, f32x4& b) const {
;         if (xin32) { a = *(const f32x4*)(xin32 + off); b = *(const f32x4*)(xin32 + off + 4); }
;         else { const h16x8 h = *(const h16x8*)(xin16 + off); a = (f32x4){(float)h[0], (float)h[1], (float)h[2], (float)h[3]}; b = (f32x4){(float)h[4], (float)h[5], (float)h[6], (float)h[7]}; }
;     }
;     __device__ __forceinline__ void operator()(AccRef acc, const pg8::Unit& u, int wr, int wc, int fr_, int fq_) const {
;     ...
;         { const size_t xo_ = (size_t)row0 * DM + col0; ldx8(xo_, xc[0], xc[1]); ldx8(xo_ + 128, xc[2], xc[3]); }
; #pragma unroll
;         for (int r = 0; r < 8; ++r) {
;             const int ai = r >> 2, m = r & 3; const int row = row0 + 128 * ai + 16 * m;
;             if (r < 7) { const int rown = row0 + 128 * ((r + 1) >> 2) + 16 * ((r + 1) & 3); const size_t xo_ = (size_t)rown * DM + col0; ldx8(xo_, xn[0], xn[1]); ldx8(xo_ + 128, xn[2], xn[3]); }
.LBB0_1288:
	global_load_dwordx4 v[10:13], v[14:15], off
	global_load_dwordx4 v[124:127], v[14:15], off offset:256
	s_waitcnt vmcnt(0)
	v_cvt_f32_f16_e32 v120, v10
	v_cvt_f32_f16_sdwa v121, v10 dst_sel:DWORD dst_unused:UNUSED_PAD src0_sel:WORD_1
	v_cvt_f32_f16_e32 v122, v11
	v_cvt_f32_f16_sdwa v123, v11 dst_sel:DWORD dst_unused:UNUSED_PAD src0_sel:WORD_1
	v_cvt_f32_f16_e32 v10, v12
	v_cvt_f32_f16_sdwa v11, v12 dst_sel:DWORD dst_unused:UNUSED_PAD src0_sel:WORD_1
	v_cvt_f32_f16_e32 v12, v13
	v_cvt_f32_f16_sdwa v13, v13 dst_sel:DWORD dst_unused:UNUSED_PAD src0_sel:WORD_1

;     __device__ __forceinline__ void ldx8(size_t off, f32x4& a, f32x4& b) const {
;         if (xin32) { a = *(const f32x4*)(xin32 + off); b = *(const f32x4*)(xin32 + off + 4); }
;         else { const h16x8 h = *(const h16x8*)(xin16 + off); a = (f32x4){(float)h[0], (float)h[1], (float)h[2], (float)h[3]}; b = (f32x4){(float)h[4], (float)h[5], (float)h[6], (float)h[7]}; }
;     }
;     __device__ __forceinline__ void operator()(AccRef acc, const pg8::Unit& u, int wr, int wc, int fr_, int fq_) const {
;     ...
;         { const size_t xo_ = (size_t)row0 * DM + col0; ldx8(xo_, xc[0], xc[1]); ldx8(xo_ + 128, xc[2], xc[3]); }
; #pragma unroll
;         for (int r = 0; r < 8; ++r) {
;             const int ai = r >> 2, m = r & 3; const int row = row0 + 128 * ai + 16 * m;
;             if (r < 7) { const int rown = row0 + 128 * ((r + 1) >> 2) + 16 * ((r + 1) & 3); const size_t xo_ = (size_t)rown * DM + col0; ldx8(xo_, xn[0], xn[1]); ldx8(xo_ + 128, xn[2], xn[3]); }
.LBB0_1291:
	v_cvt_f32_f16_e32 v128, v124
	v_cvt_f32_f16_sdwa v129, v124 dst_sel:DWORD dst_unused:UNUSED_PAD src0_sel:WORD_1
	v_cvt_f32_f16_e32 v130, v125
	v_cvt_f32_f16_sdwa v131, v125 dst_sel:DWORD dst_unused:UNUSED_PAD src0_sel:WORD_1
	v_cvt_f32_f16_e32 v124, v126
	v_cvt_f32_f16_sdwa v125, v126 dst_sel:DWORD dst_unused:UNUSED_PAD src0_sel:WORD_1
	v_cvt_f32_f16_e32 v126, v127
	v_cvt_f32_f16_sdwa v127, v127 dst_sel:DWORD dst_unused:UNUSED_PAD src0_sel:WORD_1

;     __device__ __forceinline__ void ldx8(size_t off, f32x4& a, f32x4& b) const {
;         if (xin32) { a = *(const f32x4*)(xin32 + off); b = *(const f32x4*)(xin32 + off + 4); }
;         else { const h16x8 h = *(const h16x8*)(xin16 + off); a = (f32x4){(float)h[0], (float)h[1], (float)h[2], (float)h[3]}; b = (f32x4){(float)h[4], (float)h[5], (float)h[6], (float)h[7]}; }
;     }
;     __device__ __forceinline__ void operator()(AccRef acc, const pg8::Unit& u, int wr, int wc, int fr_, int fq_) const {
;     ...
;         { const size_t xo_ = (size_t)row0 * DM + col0; ldx8(xo_, xc[0], xc[1]); ldx8(xo_ + 128, xc[2], xc[3]); }
; #pragma unroll
;         for (int r = 0; r < 8; ++r) {
;             const int ai = r >> 2, m = r & 3; const int row = row0 + 128 * ai + 16 * m;
;             if (r < 7) { const int rown = row0 + 128 * ((r + 1) >> 2) + 16 * ((r + 1) & 3); const size_t xo_ = (size_t)rown * DM + col0; ldx8(xo_, xn[0], xn[1]); ldx8(xo_ + 128, xn[2], xn[3]); }
.LBB0_1298:
	global_load_dwordx4 v[104:107], v[136:137], off
	global_load_dwordx4 v[112:115], v[136:137], off offset:256
	s_waitcnt vmcnt(0)
	v_cvt_f32_f16_e32 v108, v104
	v_cvt_f32_f16_sdwa v109, v104 dst_sel:DWORD dst_unused:UNUSED_PAD src0_sel:WORD_1
	v_cvt_f32_f16_e32 v110, v105
	v_cvt_f32_f16_sdwa v111, v105 dst_sel:DWORD dst_unused:UNUSED_PAD src0_sel:WORD_1
	v_cvt_f32_f16_e32 v104, v106
	v_cvt_f32_f16_sdwa v105, v106 dst_sel:DWORD dst_unused:UNUSED_PAD src0_sel:WORD_1
	v_cvt_f32_f16_e32 v106, v107
	v_cvt_f32_f16_sdwa v107, v107 dst_sel:DWORD dst_unused:UNUSED_PAD src0_sel:WORD_1

;     __device__ __forceinline__ void ldx8(size_t off, f32x4& a, f32x4& b) const {
;         if (xin32) { a = *(const f32x4*)(xin32 + off); b = *(const f32x4*)(xin32 + off + 4); }
;         else { const h16x8 h = *(const h16x8*)(xin16 + off); a = (f32x4){(float)h[0], (float)h[1], (float)h[2], (float)h[3]}; b = (f32x4){(float)h[4], (float)h[5], (float)h[6], (float)h[7]}; }
;     }
;     __device__ __forceinline__ void operator()(AccRef acc, const pg8::Unit& u, int wr, int wc, int fr_, int fq_) const {
;     ...
;         { const size_t xo_ = (size_t)row0 * DM + col0; ldx8(xo_, xc[0], xc[1]); ldx8(xo_ + 128, xc[2], xc[3]); }
; #pragma unroll
;         for (int r = 0; r < 8; ++r) {
;             const int ai = r >> 2, m = r & 3; const int row = row0 + 128 * ai + 16 * m;
;             if (r < 7) { const int rown = row0 + 128 * ((r + 1) >> 2) + 16 * ((r + 1) & 3); const size_t xo_ = (size_t)rown * DM + col0; ldx8(xo_, xn[0], xn[1]); ldx8(xo_ + 128, xn[2], xn[3]); }
.LBB0_1301:
	v_cvt_f32_f16_e32 v116, v112
	v_cvt_f32_f16_sdwa v117, v112 dst_sel:DWORD dst_unused:UNUSED_PAD src0_sel:WORD_1
	v_cvt_f32_f16_e32 v118, v113
	v_cvt_f32_f16_sdwa v119, v113 dst_sel:DWORD dst_unused:UNUSED_PAD src0_sel:WORD_1
	v_cvt_f32_f16_e32 v112, v114
	v_cvt_f32_f16_sdwa v113, v114 dst_sel:DWORD dst_unused:UNUSED_PAD src0_sel:WORD_1
	v_cvt_f32_f16_e32 v114, v115
	v_cvt_f32_f16_sdwa v115, v115 dst_sel:DWORD dst_unused:UNUSED_PAD src0_sel:WORD_1

;     __device__ __forceinline__ void ldx8(size_t off, f32x4& a, f32x4& b) const {
;         if (xin32) { a = *(const f32x4*)(xin32 + off); b = *(const f32x4*)(xin32 + off + 4); }
;         else { const h16x8 h = *(const h16x8*)(xin16 + off); a = (f32x4){(float)h[0], (float)h[1], (float)h[2], (float)h[3]}; b = (f32x4){(float)h[4], (float)h[5], (float)h[6], (float)h[7]}; }
;     }
;     __device__ __forceinline__ void operator()(AccRef acc, const pg8::Unit& u, int wr, int wc, int fr_, int fq_) const {
;     ...
;         { const size_t xo_ = (size_t)row0 * DM + col0; ldx8(xo_, xc[0], xc[1]); ldx8(xo_ + 128, xc[2], xc[3]); }
; #pragma unroll
;         for (int r = 0; r < 8; ++r) {
;             const int ai = r >> 2, m = r & 3; const int row = row0 + 128 * ai + 16 * m;
;             if (r < 7) { const int rown = row0 + 128 * ((r + 1) >> 2) + 16 * ((r + 1) & 3); const size_t xo_ = (size_t)rown * DM + col0; ldx8(xo_, xn[0], xn[1]); ldx8(xo_ + 128, xn[2], xn[3]); }
.LBB0_1308:
	global_load_dwordx4 v[10:13], v[102:103], off
	global_load_dwordx4 v[92:95], v[102:103], off offset:256
	s_waitcnt vmcnt(0)
	v_cvt_f32_f16_e32 v88, v10
	v_cvt_f32_f16_sdwa v89, v10 dst_sel:DWORD dst_unused:UNUSED_PAD src0_sel:WORD_1
	v_cvt_f32_f16_e32 v90, v11
	v_cvt_f32_f16_sdwa v91, v11 dst_sel:DWORD dst_unused:UNUSED_PAD src0_sel:WORD_1
	v_cvt_f32_f16_e32 v10, v12
	v_cvt_f32_f16_sdwa v11, v12 dst_sel:DWORD dst_unused:UNUSED_PAD src0_sel:WORD_1
	v_cvt_f32_f16_e32 v12, v13
	v_cvt_f32_f16_sdwa v13, v13 dst_sel:DWORD dst_unused:UNUSED_PAD src0_sel:WORD_1

;     __device__ __forceinline__ void ldx8(size_t off, f32x4& a, f32x4& b) const {
;         if (xin32) { a = *(const f32x4*)(xin32 + off); b = *(const f32x4*)(xin32 + off + 4); }
;         else { const h16x8 h = *(const h16x8*)(xin16 + off); a = (f32x4){(float)h[0], (float)h[1], (float)h[2], (float)h[3]}; b = (f32x4){(float)h[4], (float)h[5], (float)h[6], (float)h[7]}; }
;     }
;     __device__ __forceinline__ void operator()(AccRef acc, const pg8::Unit& u, int wr, int wc, int fr_, int fq_) const {
;     ...
;         { const size_t xo_ = (size_t)row0 * DM + col0; ldx8(xo_, xc[0], xc[1]); ldx8(xo_ + 128, xc[2], xc[3]); }
; #pragma unroll
;         for (int r = 0; r < 8; ++r) {
;             const int ai = r >> 2, m = r & 3; const int row = row0 + 128 * ai + 16 * m;
;             if (r < 7) { const int rown = row0 + 128 * ((r + 1) >> 2) + 16 * ((r + 1) & 3); const size_t xo_ = (size_t)rown * DM + col0; ldx8(xo_, xn[0], xn[1]); ldx8(xo_ + 128, xn[2], xn[3]); }
.LBB0_1311:
	v_cvt_f32_f16_e32 v96, v92
	v_cvt_f32_f16_sdwa v97, v92 dst_sel:DWORD dst_unused:UNUSED_PAD src0_sel:WORD_1
	v_cvt_f32_f16_e32 v98, v93
	v_cvt_f32_f16_sdwa v99, v93 dst_sel:DWORD dst_unused:UNUSED_PAD src0_sel:WORD_1
	v_cvt_f32_f16_e32 v92, v94
	v_cvt_f32_f16_sdwa v93, v94 dst_sel:DWORD dst_unused:UNUSED_PAD src0_sel:WORD_1
	v_cvt_f32_f16_e32 v94, v95
	v_cvt_f32_f16_sdwa v95, v95 dst_sel:DWORD dst_unused:UNUSED_PAD src0_sel:WORD_1

;     __device__ __forceinline__ void ldx8(size_t off, f32x4& a, f32x4& b) const {
;         if (xin32) { a = *(const f32x4*)(xin32 + off); b = *(const f32x4*)(xin32 + off + 4); }
;         else { const h16x8 h = *(const h16x8*)(xin16 + off); a = (f32x4){(float)h[0], (float)h[1], (float)h[2], (float)h[3]}; b = (f32x4){(float)h[4], (float)h[5], (float)h[6], (float)h[7]}; }
;     }
;     __device__ __forceinline__ void operator()(AccRef acc, const pg8::Unit& u, int wr, int wc, int fr_, int fq_) const {
;     ...
;         { const size_t xo_ = (size_t)row0 * DM + col0; ldx8(xo_, xc[0], xc[1]); ldx8(xo_ + 128, xc[2], xc[3]); }
; #pragma unroll
;         for (int r = 0; r < 8; ++r) {
;             const int ai = r >> 2, m = r & 3; const int row = row0 + 128 * ai + 16 * m;
;             if (r < 7) { const int rown = row0 + 128 * ((r + 1) >> 2) + 16 * ((r + 1) & 3); const size_t xo_ = (size_t)rown * DM + col0; ldx8(xo_, xn[0], xn[1]); ldx8(xo_ + 128, xn[2], xn[3]); }
.LBB0_1318:
	global_load_dwordx4 v[60:63], v[104:105], off
	global_load_dwordx4 v[80:83], v[104:105], off offset:256
	s_waitcnt vmcnt(0)
	v_cvt_f32_f16_e32 v72, v60
	v_cvt_f32_f16_sdwa v73, v60 dst_sel:DWORD dst_unused:UNUSED_PAD src0_sel:WORD_1
	v_cvt_f32_f16_e32 v74, v61
	v_cvt_f32_f16_sdwa v75, v61 dst_sel:DWORD dst_unused:UNUSED_PAD src0_sel:WORD_1
	v_cvt_f32_f16_e32 v60, v62
	v_cvt_f32_f16_sdwa v61, v62 dst_sel:DWORD dst_unused:UNUSED_PAD src0_sel:WORD_1
	v_cvt_f32_f16_e32 v62, v63
	v_cvt_f32_f16_sdwa v63, v63 dst_sel:DWORD dst_unused:UNUSED_PAD src0_sel:WORD_1

;     __device__ __forceinline__ void ldx8(size_t off, f32x4& a, f32x4& b) const {
;         if (xin32) { a = *(const f32x4*)(xin32 + off); b = *(const f32x4*)(xin32 + off + 4); }
;         else { const h16x8 h = *(const h16x8*)(xin16 + off); a = (f32x4){(float)h[0], (float)h[1], (float)h[2], (float)h[3]}; b = (f32x4){(float)h[4], (float)h[5], (float)h[6], (float)h[7]}; }
;     }
;     __device__ __forceinline__ void operator()(AccRef acc, const pg8::Unit& u, int wr, int wc, int fr_, int fq_) const {
;     ...
;         { const size_t xo_ = (size_t)row0 * DM + col0; ldx8(xo_, xc[0], xc[1]); ldx8(xo_ + 128, xc[2], xc[3]); }
; #pragma unroll
;         for (int r = 0; r < 8; ++r) {
;             const int ai = r >> 2, m = r & 3; const int row = row0 + 128 * ai + 16 * m;
;             if (r < 7) { const int rown = row0 + 128 * ((r + 1) >> 2) + 16 * ((r + 1) & 3); const size_t xo_ = (size_t)rown * DM + col0; ldx8(xo_, xn[0], xn[1]); ldx8(xo_ + 128, xn[2], xn[3]); }
.LBB0_1321:
	v_cvt_f32_f16_e32 v84, v80
	v_cvt_f32_f16_sdwa v85, v80 dst_sel:DWORD dst_unused:UNUSED_PAD src0_sel:WORD_1
	v_cvt_f32_f16_e32 v86, v81
	v_cvt_f32_f16_sdwa v87, v81 dst_sel:DWORD dst_unused:UNUSED_PAD src0_sel:WORD_1
	v_cvt_f32_f16_e32 v80, v82
	v_cvt_f32_f16_sdwa v81, v82 dst_sel:DWORD dst_unused:UNUSED_PAD src0_sel:WORD_1
	v_cvt_f32_f16_e32 v82, v83
	v_cvt_f32_f16_sdwa v83, v83 dst_sel:DWORD dst_unused:UNUSED_PAD src0_sel:WORD_1

;     __device__ __forceinline__ void ldx8(size_t off, f32x4& a, f32x4& b) const {
;         if (xin32) { a = *(const f32x4*)(xin32 + off); b = *(const f32x4*)(xin32 + off + 4); }
;         else { const h16x8 h = *(const h16x8*)(xin16 + off); a = (f32x4){(float)h[0], (float)h[1], (float)h[2], (float)h[3]}; b = (f32x4){(float)h[4], (float)h[5], (float)h[6], (float)h[7]}; }
;     }
;     __device__ __forceinline__ void operator()(AccRef acc, const pg8::Unit& u, int wr, int wc, int fr_, int fq_) const {
;     ...
;         { const size_t xo_ = (size_t)row0 * DM + col0; ldx8(xo_, xc[0], xc[1]); ldx8(xo_ + 128, xc[2], xc[3]); }
; #pragma unroll
;         for (int r = 0; r < 8; ++r) {
;             const int ai = r >> 2, m = r & 3; const int row = row0 + 128 * ai + 16 * m;
;             if (r < 7) { const int rown = row0 + 128 * ((r + 1) >> 2) + 16 * ((r + 1) & 3); const size_t xo_ = (size_t)rown * DM + col0; ldx8(xo_, xn[0], xn[1]); ldx8(xo_ + 128, xn[2], xn[3]); }
.LBB0_1328:
	global_load_dwordx4 v[40:43], v[52:53], off
	global_load_dwordx4 v[10:13], v[52:53], off offset:256
	s_waitcnt vmcnt(0)
	v_cvt_f32_f16_e32 v48, v40
	v_cvt_f32_f16_sdwa v49, v40 dst_sel:DWORD dst_unused:UNUSED_PAD src0_sel:WORD_1
	v_cvt_f32_f16_e32 v50, v41
	v_cvt_f32_f16_sdwa v51, v41 dst_sel:DWORD dst_unused:UNUSED_PAD src0_sel:WORD_1
	v_cvt_f32_f16_e32 v44, v42
	v_cvt_f32_f16_sdwa v45, v42 dst_sel:DWORD dst_unused:UNUSED_PAD src0_sel:WORD_1
	v_cvt_f32_f16_e32 v46, v43
	v_cvt_f32_f16_sdwa v47, v43 dst_sel:DWORD dst_unused:UNUSED_PAD src0_sel:WORD_1

;     __device__ __forceinline__ void ldx8(size_t off, f32x4& a, f32x4& b) const {
;         if (xin32) { a = *(const f32x4*)(xin32 + off); b = *(const f32x4*)(xin32 + off + 4); }
;         else { const h16x8 h = *(const h16x8*)(xin16 + off); a = (f32x4){(float)h[0], (float)h[1], (float)h[2], (float)h[3]}; b = (f32x4){(float)h[4], (float)h[5], (float)h[6], (float)h[7]}; }
;     }
;     __device__ __forceinline__ void operator()(AccRef acc, const pg8::Unit& u, int wr, int wc, int fr_, int fq_) const {
;     ...
;         { const size_t xo_ = (size_t)row0 * DM + col0; ldx8(xo_, xc[0], xc[1]); ldx8(xo_ + 128, xc[2], xc[3]); }
; #pragma unroll
;         for (int r = 0; r < 8; ++r) {
;             const int ai = r >> 2, m = r & 3; const int row = row0 + 128 * ai + 16 * m;
;             if (r < 7) { const int rown = row0 + 128 * ((r + 1) >> 2) + 16 * ((r + 1) & 3); const size_t xo_ = (size_t)rown * DM + col0; ldx8(xo_, xn[0], xn[1]); ldx8(xo_ + 128, xn[2], xn[3]); }
.LBB0_1331:
	v_cvt_f32_f16_e32 v40, v10
	v_cvt_f32_f16_sdwa v41, v10 dst_sel:DWORD dst_unused:UNUSED_PAD src0_sel:WORD_1
	v_cvt_f32_f16_e32 v42, v11
	v_cvt_f32_f16_sdwa v43, v11 dst_sel:DWORD dst_unused:UNUSED_PAD src0_sel:WORD_1
	v_cvt_f32_f16_e32 v10, v12
	v_cvt_f32_f16_sdwa v11, v12 dst_sel:DWORD dst_unused:UNUSED_PAD src0_sel:WORD_1
	v_cvt_f32_f16_e32 v12, v13
	v_cvt_f32_f16_sdwa v13, v13 dst_sel:DWORD dst_unused:UNUSED_PAD src0_sel:WORD_1
